# diff-attention combine: drop the per-wave buffer_inv sc1 (the scratch loads are sc0 sc1 and bypass L1 already); on top of seam-0 xcd barrier + combine batching + rss hoist
# speedup vs baseline: 1.0226x; 1.0141x over previous
; __global__ void __launch_bounds__(NWAVES * 64, 2) mk_fwd(Args args) {
;     ...
;                     if (diff) {
;                         asm volatile("s_waitcnt vmcnt(0)" ::: "memory");
;                         __builtin_amdgcn_fence(__ATOMIC_ACQUIRE, "agent");
;                         const int r = wave * 32 + (lane >> 1), c0 = (lane & 1) * 64;
;                         const bf16* s1 = scrg + r * 256 + c0; const bf16* s2 = s1 + 128;
;                         float ss = 0.f;
; #pragma unroll
;                         for (int c = 0; c < 8; ++c) { const v4u a = *(const volatile v4u*)(s1 + 8 * c), bq = *(const volatile v4u*)(s2 + 8 * c);
; #pragma unroll
;                             for (int e = 0; e < 4; ++e) { const float d0 = __uint_as_float(a[e] << 16) - lam * __uint_as_float(bq[e] << 16), d1 = __uint_as_float(a[e] & 0xffff0000u) - lam * __uint_as_float(bq[e] & 0xffff0000u); ss += d0 * d0 + d1 * d1; } }
;                         ss += __shfl_xor(ss, 1);
;                         const float rn = __builtin_amdgcn_rsqf(ss * (1.0f / 128.0f) + 1e-5f) * oml;
;                         bf16* mo = MIX + (size_t)(rowbase + q0 + r) * DM + 512 + h * 128 + c0;
; #pragma unroll
;                         for (int c = 0; c < 8; ++c) { const v4u a = *(const volatile v4u*)(s1 + 8 * c), bq = *(const volatile v4u*)(s2 + 8 * c);
;                             const f32x4 g0 = *(const f32x4*)(gsub + c0 + 8 * c), g1 = *(const f32x4*)(gsub + c0 + 8 * c + 4); v4u o;
.LBB0_364:
	s_and_b64 vcc, exec, s[4:5]
	s_cbranch_vccnz .LBB0_269
	s_waitcnt vmcnt(0)
	s_waitcnt vmcnt(0)
	s_nop 0
	global_load_dwordx4 v[60:63], v[216:217], off sc0 sc1
	global_load_dwordx4 v[64:67], v[216:217], off offset:256 sc0 sc1
	global_load_dwordx4 v[68:71], v[216:217], off offset:16 sc0 sc1
	global_load_dwordx4 v[72:75], v[216:217], off offset:272 sc0 sc1
	global_load_dwordx4 v[76:79], v[216:217], off offset:32 sc0 sc1
	global_load_dwordx4 v[80:83], v[216:217], off offset:288 sc0 sc1
	global_load_dwordx4 v[84:87], v[216:217], off offset:48 sc0 sc1
	global_load_dwordx4 v[88:91], v[216:217], off offset:304 sc0 sc1
	global_load_dwordx4 v[92:95], v[216:217], off offset:64 sc0 sc1
	global_load_dwordx4 v[96:99], v[216:217], off offset:320 sc0 sc1
	global_load_dwordx4 v[100:103], v[216:217], off offset:80 sc0 sc1
	global_load_dwordx4 v[104:107], v[216:217], off offset:336 sc0 sc1
	global_load_dwordx4 v[108:111], v[216:217], off offset:96 sc0 sc1
	global_load_dwordx4 v[112:115], v[216:217], off offset:352 sc0 sc1
	global_load_dwordx4 v[116:119], v[216:217], off offset:112 sc0 sc1
	global_load_dwordx4 v[120:123], v[216:217], off offset:368 sc0 sc1
	global_load_dwordx4 v[124:127], v[220:221], off
	global_load_dwordx4 v[128:131], v[220:221], off offset:16
	global_load_dwordx4 v[132:135], v[220:221], off offset:32
	global_load_dwordx4 v[136:139], v[220:221], off offset:48
	global_load_dwordx4 v[140:143], v[220:221], off offset:64
	global_load_dwordx4 v[144:147], v[220:221], off offset:80
	global_load_dwordx4 v[148:151], v[220:221], off offset:96
	global_load_dwordx4 v[152:155], v[220:221], off offset:112
	global_load_dwordx4 v[156:159], v[220:221], off offset:128
	global_load_dwordx4 v[160:163], v[220:221], off offset:144
	global_load_dwordx4 v[164:167], v[220:221], off offset:160
	global_load_dwordx4 v[168:171], v[220:221], off offset:176
	global_load_dwordx4 v[172:175], v[220:221], off offset:192
	global_load_dwordx4 v[176:179], v[220:221], off offset:208
	global_load_dwordx4 v[180:183], v[220:221], off offset:224
	global_load_dwordx4 v[184:187], v[220:221], off offset:240
	s_lshl_b32 s8, s87, 8
	v_mov_b32_e32 v223, v1
	v_add_u32_e32 v2, s68, v239
	v_ashrrev_i32_e32 v3, 31, v2
	v_lshlrev_b64 v[2:3], 11, v[2:3]
	v_lshl_add_u64 v[2:3], s[36:37], 0, v[2:3]
	v_lshl_add_u64 v[2:3], v[2:3], 0, s[8:9]
	v_lshl_add_u64 v[2:3], v[2:3], 0, v[222:223]
	v_mov_b32_e32 v12, 0
	v_mov_b32_e32 v13, 0
	v_mov_b32_e32 v14, 0
	v_mov_b32_e32 v15, 0
	s_waitcnt vmcnt(30)
	v_lshlrev_b32_e32 v4, 16, v60
	v_lshlrev_b32_e32 v5, 16, v64
	v_and_b32_e32 v60, s84, v60
	v_and_b32_e32 v64, s84, v64
	v_fma_f32 v60, -v218, v64, v60
	v_fma_f32 v64, -v218, v5, v4
	v_fmac_f32_e32 v12, v60, v60
	v_fmac_f32_e32 v12, v64, v64
	v_lshlrev_b32_e32 v6, 16, v61
	v_lshlrev_b32_e32 v7, 16, v65
	v_and_b32_e32 v61, s84, v61
	v_and_b32_e32 v65, s84, v65
	v_fma_f32 v61, -v218, v65, v61
	v_fma_f32 v65, -v218, v7, v6
	v_fmac_f32_e32 v13, v61, v61
	v_fmac_f32_e32 v13, v65, v65
	v_lshlrev_b32_e32 v8, 16, v62
	v_lshlrev_b32_e32 v9, 16, v66
	v_and_b32_e32 v62, s84, v62
	v_and_b32_e32 v66, s84, v66
	v_fma_f32 v62, -v218, v66, v62
	v_fma_f32 v66, -v218, v9, v8
	v_fmac_f32_e32 v14, v62, v62
	v_fmac_f32_e32 v14, v66, v66
	v_lshlrev_b32_e32 v10, 16, v63
	v_lshlrev_b32_e32 v11, 16, v67
	v_and_b32_e32 v63, s84, v63
	v_and_b32_e32 v67, s84, v67
	v_fma_f32 v63, -v218, v67, v63
	v_fma_f32 v67, -v218, v11, v10
	v_fmac_f32_e32 v15, v63, v63
	v_fmac_f32_e32 v15, v67, v67
	s_waitcnt vmcnt(28)
	v_lshlrev_b32_e32 v4, 16, v68
	v_lshlrev_b32_e32 v5, 16, v72
	v_and_b32_e32 v68, s84, v68
	v_and_b32_e32 v72, s84, v72
	v_fma_f32 v68, -v218, v72, v68
	v_fma_f32 v72, -v218, v5, v4
	v_fmac_f32_e32 v12, v68, v68
	v_fmac_f32_e32 v12, v72, v72
	v_lshlrev_b32_e32 v6, 16, v69
	v_lshlrev_b32_e32 v7, 16, v73
	v_and_b32_e32 v69, s84, v69
	v_and_b32_e32 v73, s84, v73
	v_fma_f32 v69, -v218, v73, v69
	v_fma_f32 v73, -v218, v7, v6
	v_fmac_f32_e32 v13, v69, v69
	v_fmac_f32_e32 v13, v73, v73
	v_lshlrev_b32_e32 v8, 16, v70
	v_lshlrev_b32_e32 v9, 16, v74
	v_and_b32_e32 v70, s84, v70
	v_and_b32_e32 v74, s84, v74
	v_fma_f32 v70, -v218, v74, v70
	v_fma_f32 v74, -v218, v9, v8
	v_fmac_f32_e32 v14, v70, v70
	v_fmac_f32_e32 v14, v74, v74
	v_lshlrev_b32_e32 v10, 16, v71
	v_lshlrev_b32_e32 v11, 16, v75
	v_and_b32_e32 v71, s84, v71
	v_and_b32_e32 v75, s84, v75
	v_fma_f32 v71, -v218, v75, v71
	v_fma_f32 v75, -v218, v11, v10
	v_fmac_f32_e32 v15, v71, v71
	v_fmac_f32_e32 v15, v75, v75
	s_waitcnt vmcnt(26)
	v_lshlrev_b32_e32 v4, 16, v76
	v_lshlrev_b32_e32 v5, 16, v80
	v_and_b32_e32 v76, s84, v76
	v_and_b32_e32 v80, s84, v80
	v_fma_f32 v76, -v218, v80, v76
	v_fma_f32 v80, -v218, v5, v4
	v_fmac_f32_e32 v12, v76, v76
	v_fmac_f32_e32 v12, v80, v80
	v_lshlrev_b32_e32 v6, 16, v77
	v_lshlrev_b32_e32 v7, 16, v81
	v_and_b32_e32 v77, s84, v77
	v_and_b32_e32 v81, s84, v81
	v_fma_f32 v77, -v218, v81, v77
	v_fma_f32 v81, -v218, v7, v6
	v_fmac_f32_e32 v13, v77, v77
	v_fmac_f32_e32 v13, v81, v81
	v_lshlrev_b32_e32 v8, 16, v78
	v_lshlrev_b32_e32 v9, 16, v82
	v_and_b32_e32 v78, s84, v78
	v_and_b32_e32 v82, s84, v82
	v_fma_f32 v78, -v218, v82, v78
	v_fma_f32 v82, -v218, v9, v8
	v_fmac_f32_e32 v14, v78, v78
	v_fmac_f32_e32 v14, v82, v82
	v_lshlrev_b32_e32 v10, 16, v79
	v_lshlrev_b32_e32 v11, 16, v83
	v_and_b32_e32 v79, s84, v79
	v_and_b32_e32 v83, s84, v83
	v_fma_f32 v79, -v218, v83, v79
	v_fma_f32 v83, -v218, v11, v10
	v_fmac_f32_e32 v15, v79, v79
	v_fmac_f32_e32 v15, v83, v83
	s_waitcnt vmcnt(24)
; __global__ void __launch_bounds__(NWAVES * 64, 2) mk_fwd(Args args) {
;     ...
;                         for (int c = 0; c < 8; ++c) { const v4u a = *(const volatile v4u*)(s1 + 8 * c), bq = *(const volatile v4u*)(s2 + 8 * c);
; #pragma unroll
;                             for (int e = 0; e < 4; ++e) { const float d0 = __uint_as_float(a[e] << 16) - lam * __uint_as_float(bq[e] << 16), d1 = __uint_as_float(a[e] & 0xffff0000u) - lam * __uint_as_float(bq[e] & 0xffff0000u); ss += d0 * d0 + d1 * d1; } }
;                         ss += __shfl_xor(ss, 1);
;                         const float rn = __builtin_amdgcn_rsqf(ss * (1.0f / 128.0f) + 1e-5f) * oml;
	v_lshlrev_b32_e32 v4, 16, v84
	v_lshlrev_b32_e32 v5, 16, v88
	v_and_b32_e32 v84, s84, v84
	v_and_b32_e32 v88, s84, v88
	v_fma_f32 v84, -v218, v88, v84
	v_fma_f32 v88, -v218, v5, v4
	v_fmac_f32_e32 v12, v84, v84
	v_fmac_f32_e32 v12, v88, v88
	v_lshlrev_b32_e32 v6, 16, v85
	v_lshlrev_b32_e32 v7, 16, v89
	v_and_b32_e32 v85, s84, v85
	v_and_b32_e32 v89, s84, v89
	v_fma_f32 v85, -v218, v89, v85
	v_fma_f32 v89, -v218, v7, v6
	v_fmac_f32_e32 v13, v85, v85
	v_fmac_f32_e32 v13, v89, v89
	v_lshlrev_b32_e32 v8, 16, v86
	v_lshlrev_b32_e32 v9, 16, v90
	v_and_b32_e32 v86, s84, v86
	v_and_b32_e32 v90, s84, v90
	v_fma_f32 v86, -v218, v90, v86
	v_fma_f32 v90, -v218, v9, v8
	v_fmac_f32_e32 v14, v86, v86
	v_fmac_f32_e32 v14, v90, v90
	v_lshlrev_b32_e32 v10, 16, v87
	v_lshlrev_b32_e32 v11, 16, v91
	v_and_b32_e32 v87, s84, v87
	v_and_b32_e32 v91, s84, v91
	v_fma_f32 v87, -v218, v91, v87
	v_fma_f32 v91, -v218, v11, v10
	v_fmac_f32_e32 v15, v87, v87
	v_fmac_f32_e32 v15, v91, v91
	s_waitcnt vmcnt(22)
	v_lshlrev_b32_e32 v4, 16, v92
	v_lshlrev_b32_e32 v5, 16, v96
	v_and_b32_e32 v92, s84, v92
	v_and_b32_e32 v96, s84, v96
	v_fma_f32 v92, -v218, v96, v92
	v_fma_f32 v96, -v218, v5, v4
	v_fmac_f32_e32 v12, v92, v92
	v_fmac_f32_e32 v12, v96, v96
	v_lshlrev_b32_e32 v6, 16, v93
	v_lshlrev_b32_e32 v7, 16, v97
	v_and_b32_e32 v93, s84, v93
	v_and_b32_e32 v97, s84, v97
	v_fma_f32 v93, -v218, v97, v93
	v_fma_f32 v97, -v218, v7, v6
	v_fmac_f32_e32 v13, v93, v93
	v_fmac_f32_e32 v13, v97, v97
	v_lshlrev_b32_e32 v8, 16, v94
	v_lshlrev_b32_e32 v9, 16, v98
	v_and_b32_e32 v94, s84, v94
	v_and_b32_e32 v98, s84, v98
	v_fma_f32 v94, -v218, v98, v94
	v_fma_f32 v98, -v218, v9, v8
	v_fmac_f32_e32 v14, v94, v94
	v_fmac_f32_e32 v14, v98, v98
	v_lshlrev_b32_e32 v10, 16, v95
	v_lshlrev_b32_e32 v11, 16, v99
	v_and_b32_e32 v95, s84, v95
	v_and_b32_e32 v99, s84, v99
	v_fma_f32 v95, -v218, v99, v95
	v_fma_f32 v99, -v218, v11, v10
	v_fmac_f32_e32 v15, v95, v95
	v_fmac_f32_e32 v15, v99, v99
	s_waitcnt vmcnt(20)
	v_lshlrev_b32_e32 v4, 16, v100
	v_lshlrev_b32_e32 v5, 16, v104
	v_and_b32_e32 v100, s84, v100
	v_and_b32_e32 v104, s84, v104
	v_fma_f32 v100, -v218, v104, v100
	v_fma_f32 v104, -v218, v5, v4
	v_fmac_f32_e32 v12, v100, v100
	v_fmac_f32_e32 v12, v104, v104
	v_lshlrev_b32_e32 v6, 16, v101
	v_lshlrev_b32_e32 v7, 16, v105
	v_and_b32_e32 v101, s84, v101
	v_and_b32_e32 v105, s84, v105
	v_fma_f32 v101, -v218, v105, v101
	v_fma_f32 v105, -v218, v7, v6
	v_fmac_f32_e32 v13, v101, v101
	v_fmac_f32_e32 v13, v105, v105
	v_lshlrev_b32_e32 v8, 16, v102
	v_lshlrev_b32_e32 v9, 16, v106
	v_and_b32_e32 v102, s84, v102
	v_and_b32_e32 v106, s84, v106
	v_fma_f32 v102, -v218, v106, v102
	v_fma_f32 v106, -v218, v9, v8
	v_fmac_f32_e32 v14, v102, v102
	v_fmac_f32_e32 v14, v106, v106
	v_lshlrev_b32_e32 v10, 16, v103
	v_lshlrev_b32_e32 v11, 16, v107
	v_and_b32_e32 v103, s84, v103
	v_and_b32_e32 v107, s84, v107
	v_fma_f32 v103, -v218, v107, v103
	v_fma_f32 v107, -v218, v11, v10
	v_fmac_f32_e32 v15, v103, v103
	v_fmac_f32_e32 v15, v107, v107
	s_waitcnt vmcnt(18)
	v_lshlrev_b32_e32 v4, 16, v108
	v_lshlrev_b32_e32 v5, 16, v112
	v_and_b32_e32 v108, s84, v108
	v_and_b32_e32 v112, s84, v112
	v_fma_f32 v108, -v218, v112, v108
	v_fma_f32 v112, -v218, v5, v4
	v_fmac_f32_e32 v12, v108, v108
	v_fmac_f32_e32 v12, v112, v112
	v_lshlrev_b32_e32 v6, 16, v109
	v_lshlrev_b32_e32 v7, 16, v113
	v_and_b32_e32 v109, s84, v109
	v_and_b32_e32 v113, s84, v113
	v_fma_f32 v109, -v218, v113, v109
	v_fma_f32 v113, -v218, v7, v6
	v_fmac_f32_e32 v13, v109, v109
	v_fmac_f32_e32 v13, v113, v113
	v_lshlrev_b32_e32 v8, 16, v110
	v_lshlrev_b32_e32 v9, 16, v114
	v_and_b32_e32 v110, s84, v110
	v_and_b32_e32 v114, s84, v114
	v_fma_f32 v110, -v218, v114, v110
	v_fma_f32 v114, -v218, v9, v8
	v_fmac_f32_e32 v14, v110, v110
	v_fmac_f32_e32 v14, v114, v114
	v_lshlrev_b32_e32 v10, 16, v111
	v_lshlrev_b32_e32 v11, 16, v115
	v_and_b32_e32 v111, s84, v111
	v_and_b32_e32 v115, s84, v115
	v_fma_f32 v111, -v218, v115, v111
	v_fma_f32 v115, -v218, v11, v10
	v_fmac_f32_e32 v15, v111, v111
	v_fmac_f32_e32 v15, v115, v115
	s_waitcnt vmcnt(16)
	v_lshlrev_b32_e32 v4, 16, v116
	v_lshlrev_b32_e32 v5, 16, v120
	v_and_b32_e32 v116, s84, v116
	v_and_b32_e32 v120, s84, v120
	v_fma_f32 v116, -v218, v120, v116
	v_fma_f32 v120, -v218, v5, v4
	v_fmac_f32_e32 v12, v116, v116
	v_fmac_f32_e32 v12, v120, v120
	v_lshlrev_b32_e32 v6, 16, v117
	v_lshlrev_b32_e32 v7, 16, v121
	v_and_b32_e32 v117, s84, v117
	v_and_b32_e32 v121, s84, v121
	v_fma_f32 v117, -v218, v121, v117
	v_fma_f32 v121, -v218, v7, v6
	v_fmac_f32_e32 v13, v117, v117
	v_fmac_f32_e32 v13, v121, v121
	v_lshlrev_b32_e32 v8, 16, v118
	v_lshlrev_b32_e32 v9, 16, v122
	v_and_b32_e32 v118, s84, v118
	v_and_b32_e32 v122, s84, v122
	v_fma_f32 v118, -v218, v122, v118
	v_fma_f32 v122, -v218, v9, v8
	v_fmac_f32_e32 v14, v118, v118
	v_fmac_f32_e32 v14, v122, v122
	v_lshlrev_b32_e32 v10, 16, v119
	v_lshlrev_b32_e32 v11, 16, v123
	v_and_b32_e32 v119, s84, v119
	v_and_b32_e32 v123, s84, v123
	v_fma_f32 v119, -v218, v123, v119
	v_fma_f32 v123, -v218, v11, v10
	v_fmac_f32_e32 v15, v119, v119
	v_fmac_f32_e32 v15, v123, v123
	v_add_f32_e32 v12, v12, v13
	v_add_f32_e32 v14, v14, v15
	v_add_f32_e32 v0, v12, v14
	s_nop 0
	ds_bpermute_b32 v4, v240, v0
	s_waitcnt lgkmcnt(0)
	v_add_f32_e32 v0, v0, v4
	v_fmamk_f32 v0, v0, 0x3c000000, v242
	v_rsq_f32_e32 v0, v0
	s_nop 1
	v_mul_f32_e32 v0, 0x3f4ccccd, v0
	s_waitcnt vmcnt(0)
; __device__ __forceinline__ unsigned pk2(float lo, float hi) { return f2bf(lo) | (f2bf(hi) << 16); }
; __global__ void __launch_bounds__(NWAVES * 64, 2) mk_fwd(Args args) {
;     ...
;                         bf16* mo = MIX + (size_t)(rowbase + q0 + r) * DM + 512 + h * 128 + c0;
; #pragma unroll
;                         for (int c = 0; c < 8; ++c) { const v4u a = *(const volatile v4u*)(s1 + 8 * c), bq = *(const volatile v4u*)(s2 + 8 * c);
;                             const f32x4 g0 = *(const f32x4*)(gsub + c0 + 8 * c), g1 = *(const f32x4*)(gsub + c0 + 8 * c + 4); v4u o;
; #pragma unroll
;                             for (int e = 0; e < 4; ++e) { const float d0 = __uint_as_float(a[e] << 16) - lam * __uint_as_float(bq[e] << 16), d1 = __uint_as_float(a[e] & 0xffff0000u) - lam * __uint_as_float(bq[e] & 0xffff0000u);
;                                 const float ga = (e < 2) ? g0[2 * e] : g1[2 * e - 4], gb = (e < 2) ? g0[2 * e + 1] : g1[2 * e - 3];
;                                 o[e] = pk2(d0 * rn * ga, d1 * rn * gb); }
;                             *(v4u*)(mo + 8 * c) = o; }
;                         asm volatile("s_waitcnt vmcnt(0)" ::: "memory");
;                         __syncthreads();
	v_mul_f32_e32 v64, v0, v64
	v_mul_f32_e32 v60, v0, v60
	v_mul_f32_e32 v64, v64, v124
	v_mul_f32_e32 v60, v60, v125
	v_cvt_pk_bf16_f32 v4, v64, v60
	v_mul_f32_e32 v65, v0, v65
	v_mul_f32_e32 v61, v0, v61
	v_mul_f32_e32 v65, v65, v126
	v_mul_f32_e32 v61, v61, v127
	v_cvt_pk_bf16_f32 v5, v65, v61
	v_mul_f32_e32 v66, v0, v66
	v_mul_f32_e32 v62, v0, v62
	v_mul_f32_e32 v66, v66, v128
	v_mul_f32_e32 v62, v62, v129
	v_cvt_pk_bf16_f32 v6, v66, v62
	v_mul_f32_e32 v67, v0, v67
	v_mul_f32_e32 v63, v0, v63
	v_mul_f32_e32 v67, v67, v130
	v_mul_f32_e32 v63, v63, v131
	v_cvt_pk_bf16_f32 v7, v67, v63
	global_store_dwordx4 v[2:3], v[4:7], off offset:1024
	v_mul_f32_e32 v72, v0, v72
	v_mul_f32_e32 v68, v0, v68
	v_mul_f32_e32 v72, v72, v132
	v_mul_f32_e32 v68, v68, v133
	v_cvt_pk_bf16_f32 v8, v72, v68
	v_mul_f32_e32 v73, v0, v73
	v_mul_f32_e32 v69, v0, v69
	v_mul_f32_e32 v73, v73, v134
	v_mul_f32_e32 v69, v69, v135
	v_cvt_pk_bf16_f32 v9, v73, v69
	v_mul_f32_e32 v74, v0, v74
	v_mul_f32_e32 v70, v0, v70
	v_mul_f32_e32 v74, v74, v136
	v_mul_f32_e32 v70, v70, v137
	v_cvt_pk_bf16_f32 v10, v74, v70
	v_mul_f32_e32 v75, v0, v75
	v_mul_f32_e32 v71, v0, v71
	v_mul_f32_e32 v75, v75, v138
	v_mul_f32_e32 v71, v71, v139
	v_cvt_pk_bf16_f32 v11, v75, v71
	global_store_dwordx4 v[2:3], v[8:11], off offset:1040
	v_mul_f32_e32 v80, v0, v80
	v_mul_f32_e32 v76, v0, v76
	v_mul_f32_e32 v80, v80, v140
	v_mul_f32_e32 v76, v76, v141
	v_cvt_pk_bf16_f32 v4, v80, v76
	v_mul_f32_e32 v81, v0, v81
	v_mul_f32_e32 v77, v0, v77
	v_mul_f32_e32 v81, v81, v142
	v_mul_f32_e32 v77, v77, v143
	v_cvt_pk_bf16_f32 v5, v81, v77
	v_mul_f32_e32 v82, v0, v82
	v_mul_f32_e32 v78, v0, v78
	v_mul_f32_e32 v82, v82, v144
	v_mul_f32_e32 v78, v78, v145
	v_cvt_pk_bf16_f32 v6, v82, v78
	v_mul_f32_e32 v83, v0, v83
	v_mul_f32_e32 v79, v0, v79
	v_mul_f32_e32 v83, v83, v146
	v_mul_f32_e32 v79, v79, v147
	v_cvt_pk_bf16_f32 v7, v83, v79
	global_store_dwordx4 v[2:3], v[4:7], off offset:1056
	v_mul_f32_e32 v88, v0, v88
	v_mul_f32_e32 v84, v0, v84
	v_mul_f32_e32 v88, v88, v148
	v_mul_f32_e32 v84, v84, v149
	v_cvt_pk_bf16_f32 v8, v88, v84
	v_mul_f32_e32 v89, v0, v89
	v_mul_f32_e32 v85, v0, v85
	v_mul_f32_e32 v89, v89, v150
	v_mul_f32_e32 v85, v85, v151
	v_cvt_pk_bf16_f32 v9, v89, v85
	v_mul_f32_e32 v90, v0, v90
	v_mul_f32_e32 v86, v0, v86
	v_mul_f32_e32 v90, v90, v152
	v_mul_f32_e32 v86, v86, v153
	v_cvt_pk_bf16_f32 v10, v90, v86
	v_mul_f32_e32 v91, v0, v91
	v_mul_f32_e32 v87, v0, v87
	v_mul_f32_e32 v91, v91, v154
	v_mul_f32_e32 v87, v87, v155
	v_cvt_pk_bf16_f32 v11, v91, v87
	global_store_dwordx4 v[2:3], v[8:11], off offset:1072
	v_mul_f32_e32 v96, v0, v96
	v_mul_f32_e32 v92, v0, v92
	v_mul_f32_e32 v96, v96, v156
	v_mul_f32_e32 v92, v92, v157
	v_cvt_pk_bf16_f32 v4, v96, v92
	v_mul_f32_e32 v97, v0, v97
	v_mul_f32_e32 v93, v0, v93
	v_mul_f32_e32 v97, v97, v158
	v_mul_f32_e32 v93, v93, v159
	v_cvt_pk_bf16_f32 v5, v97, v93
	v_mul_f32_e32 v98, v0, v98
	v_mul_f32_e32 v94, v0, v94
	v_mul_f32_e32 v98, v98, v160
	v_mul_f32_e32 v94, v94, v161
	v_cvt_pk_bf16_f32 v6, v98, v94
	v_mul_f32_e32 v99, v0, v99
	v_mul_f32_e32 v95, v0, v95
	v_mul_f32_e32 v99, v99, v162
	v_mul_f32_e32 v95, v95, v163
	v_cvt_pk_bf16_f32 v7, v99, v95
	global_store_dwordx4 v[2:3], v[4:7], off offset:1088
	v_mul_f32_e32 v104, v0, v104
	v_mul_f32_e32 v100, v0, v100
	v_mul_f32_e32 v104, v104, v164
	v_mul_f32_e32 v100, v100, v165
	v_cvt_pk_bf16_f32 v8, v104, v100
	v_mul_f32_e32 v105, v0, v105
	v_mul_f32_e32 v101, v0, v101
	v_mul_f32_e32 v105, v105, v166
	v_mul_f32_e32 v101, v101, v167
	v_cvt_pk_bf16_f32 v9, v105, v101
	v_mul_f32_e32 v106, v0, v106
	v_mul_f32_e32 v102, v0, v102
	v_mul_f32_e32 v106, v106, v168
	v_mul_f32_e32 v102, v102, v169
	v_cvt_pk_bf16_f32 v10, v106, v102
	v_mul_f32_e32 v107, v0, v107
	v_mul_f32_e32 v103, v0, v103
	v_mul_f32_e32 v107, v107, v170
	v_mul_f32_e32 v103, v103, v171
	v_cvt_pk_bf16_f32 v11, v107, v103
	global_store_dwordx4 v[2:3], v[8:11], off offset:1104
	v_mul_f32_e32 v112, v0, v112
	v_mul_f32_e32 v108, v0, v108
	v_mul_f32_e32 v112, v112, v172
	v_mul_f32_e32 v108, v108, v173
	v_cvt_pk_bf16_f32 v4, v112, v108
	v_mul_f32_e32 v113, v0, v113
	v_mul_f32_e32 v109, v0, v109
	v_mul_f32_e32 v113, v113, v174
	v_mul_f32_e32 v109, v109, v175
	v_cvt_pk_bf16_f32 v5, v113, v109
	v_mul_f32_e32 v114, v0, v114
	v_mul_f32_e32 v110, v0, v110
	v_mul_f32_e32 v114, v114, v176
	v_mul_f32_e32 v110, v110, v177
	v_cvt_pk_bf16_f32 v6, v114, v110
	v_mul_f32_e32 v115, v0, v115
	v_mul_f32_e32 v111, v0, v111
	v_mul_f32_e32 v115, v115, v178
	v_mul_f32_e32 v111, v111, v179
	v_cvt_pk_bf16_f32 v7, v115, v111
	global_store_dwordx4 v[2:3], v[4:7], off offset:1120
	v_mul_f32_e32 v120, v0, v120
	v_mul_f32_e32 v116, v0, v116
	v_mul_f32_e32 v120, v120, v180
	v_mul_f32_e32 v116, v116, v181
	v_cvt_pk_bf16_f32 v8, v120, v116
	v_mul_f32_e32 v121, v0, v121
	v_mul_f32_e32 v117, v0, v117
	v_mul_f32_e32 v121, v121, v182
	v_mul_f32_e32 v117, v117, v183
	v_cvt_pk_bf16_f32 v9, v121, v117
	v_mul_f32_e32 v122, v0, v122
	v_mul_f32_e32 v118, v0, v118
	v_mul_f32_e32 v122, v122, v184
	v_mul_f32_e32 v118, v118, v185
	v_cvt_pk_bf16_f32 v10, v122, v118
	v_mul_f32_e32 v123, v0, v123
	v_mul_f32_e32 v119, v0, v119
	v_mul_f32_e32 v123, v123, v186
	v_mul_f32_e32 v119, v119, v187
	v_cvt_pk_bf16_f32 v11, v123, v119
	global_store_dwordx4 v[2:3], v[8:11], off offset:1136
	s_waitcnt vmcnt(0)
	s_barrier
	s_branch .LBB0_269
; __global__ void __launch_bounds__(NWAVES * 64, 2) mk_fwd(Args args) {
;     ...
;                         __syncthreads();
;                     }
;                 }
	s_nop 0
	s_nop 0
	s_nop 0
	s_nop 0
	s_nop 0
	s_nop 0
	s_nop 0
	s_nop 0
	s_nop 0
	s_nop 0
	s_nop 0
	s_nop 0
	s_nop 0
	s_nop 0
	s_nop 0
	s_nop 0
	s_nop 0
	s_nop 0
	s_nop 0
	s_nop 0
	s_nop 0
	s_nop 0
	s_nop 0
	s_nop 0
	s_nop 0
	s_nop 0
	s_nop 0
	s_nop 0
	s_nop 0
	s_nop 0
	s_nop 0
	s_nop 0
	s_nop 0
	s_nop 0
	s_nop 0
	s_nop 0
	s_nop 0
	s_nop 0
	s_nop 0
	s_nop 0
	s_nop 0
	s_nop 0
	s_nop 0
	s_nop 0
	s_nop 0
	s_nop 0
	s_nop 0
	s_nop 0
	s_nop 0
	s_nop 0
	s_nop 0
	s_nop 0
	s_nop 0
	s_nop 0
	s_nop 0
	s_nop 0
	s_nop 0
	s_nop 0
	s_nop 0
	s_nop 0
	s_nop 0
	s_nop 0
	s_nop 0
	s_nop 0
	s_nop 0
	s_nop 0
	s_nop 0
	s_nop 0
	s_nop 0
	s_nop 0
	s_nop 0
	s_nop 0
	s_nop 0
	s_nop 0
	s_nop 0
	s_nop 0
	s_nop 0
	s_nop 0
	s_nop 0
	s_nop 0
	s_nop 0
	s_nop 0
	s_nop 0
	s_nop 0
	s_nop 0
	s_nop 0
	s_nop 0
	s_nop 0
	s_nop 0
	s_nop 0
	s_nop 0
	s_nop 0
	s_nop 0
	s_nop 0
	s_nop 0
	s_nop 0
	s_nop 0
	s_nop 0
	s_nop 0
	s_nop 0
	s_nop 0
	s_nop 0
	s_nop 0
	s_nop 0
	s_nop 0
	s_nop 0
	s_nop 0
	s_nop 0
	s_nop 0
	s_nop 0
	s_nop 0
	s_nop 0
	s_nop 0
	s_nop 0
	s_nop 0
	s_nop 0
	s_nop 0
	s_nop 0
	s_nop 0
	s_nop 0
	s_nop 0
	s_nop 0
	s_nop 0
	s_nop 0
	s_nop 0
	s_nop 0
	s_nop 0
	s_nop 0
	s_nop 0
	s_nop 0
	s_nop 0
	s_nop 0
	s_nop 0
	s_nop 0
	s_nop 0
	s_nop 0
	s_nop 0
	s_nop 0
	s_nop 0
	s_nop 0
	s_nop 0
	s_nop 0
	s_nop 0
	s_nop 0
	s_nop 0
	s_nop 0
	s_nop 0
	s_nop 0
	s_nop 0
	s_nop 0
	s_nop 0
	s_nop 0
	s_nop 0
	s_nop 0
	s_nop 0
	s_nop 0
	s_nop 0
	s_nop 0
	s_nop 0
	s_nop 0
	s_nop 0
	s_nop 0
	s_nop 0
	s_nop 0
	s_nop 0
	s_nop 0
	s_nop 0
	s_nop 0
	s_nop 0
	s_nop 0
	s_nop 0
	s_nop 0
	s_nop 0
	s_nop 0
	s_nop 0
	s_nop 0
	s_nop 0
	s_nop 0
	s_nop 0
	s_nop 0
	s_nop 0
	s_nop 0
	s_nop 0
	s_nop 0
	s_nop 0
	s_nop 0
	s_nop 0
	s_nop 0
	s_nop 0
	s_nop 0
	s_nop 0
	s_nop 0
	s_nop 0
	s_nop 0
	s_nop 0
	s_nop 0
	s_nop 0
	s_nop 0
	s_nop 0
	s_nop 0
	s_nop 0
	s_nop 0
	s_nop 0
	s_nop 0
	s_nop 0
	s_nop 0
	s_nop 0
	s_nop 0
	s_nop 0
	s_nop 0
	s_nop 0
	s_nop 0
	s_nop 0
	s_nop 0
	s_nop 0
	s_nop 0
	s_nop 0
	s_nop 0
	s_nop 0
	s_nop 0
	s_nop 0
	s_nop 0
	s_nop 0
	s_nop 0
	s_nop 0
	s_nop 0
	s_nop 0
	s_nop 0
	s_nop 0
	s_nop 0
	s_nop 0
	s_nop 0
	s_nop 0
	s_nop 0
	s_nop 0
	s_nop 0
	s_nop 0
	s_nop 0
	s_nop 0
	s_nop 0
	s_nop 0
	s_nop 0
	s_nop 0
	s_nop 0
	s_nop 0
	s_nop 0
	s_nop 0
	s_nop 0
	s_nop 0
	s_nop 0
	s_nop 0
	s_nop 0
	s_nop 0
	s_nop 0
	s_nop 0
	s_nop 0
	s_nop 0
	s_nop 0
	s_nop 0
	s_nop 0
	s_nop 0
	s_nop 0
	s_nop 0
	s_nop 0
	s_nop 0
	s_nop 0
	s_nop 0
	s_nop 0
	s_nop 0
	s_nop 0
	s_nop 0
	s_nop 0
	s_nop 0
	s_nop 0
	s_nop 0
	s_nop 0
	s_nop 0
	s_nop 0
	s_nop 0
	s_nop 0
	s_nop 0
	s_nop 0
	s_nop 0
	s_nop 0
	s_nop 0
	s_nop 0
	s_nop 0
	s_nop 0
	s_nop 0
	s_nop 0
	s_nop 0
	s_nop 0
	s_nop 0
	s_nop 0
	s_nop 0
	s_nop 0
	s_nop 0
	s_nop 0
	s_nop 0
	s_nop 0
	s_nop 0
	s_nop 0
	s_nop 0
	s_nop 0
	s_nop 0
	s_nop 0
	s_nop 0
	s_nop 0
	s_nop 0
	s_nop 0
	s_nop 0
	s_nop 0
	s_nop 0
	s_nop 0
	s_nop 0
	s_nop 0
	s_nop 0
	s_nop 0
	s_nop 0
	s_nop 0
	s_nop 0
	s_nop 0
	s_nop 0
	s_nop 0
	s_nop 0
	s_nop 0
	s_nop 0
	s_nop 0
	s_nop 0
	s_nop 0
	s_nop 0
	s_nop 0
	s_nop 0
	s_nop 0
	s_nop 0
	s_nop 0
	s_nop 0
	s_nop 0
	s_nop 0
	s_nop 0
	s_nop 0
	s_nop 0
	s_nop 0
	s_nop 0
	s_nop 0
	s_nop 0
	s_nop 0
	s_nop 0
	s_nop 0
	s_nop 0
	s_nop 0
	s_nop 0
	s_nop 0
	s_nop 0
	s_nop 0
	s_nop 0
	s_nop 0
	s_nop 0
	s_nop 0
	s_nop 0
	s_nop 0
	s_nop 0
	s_nop 0
	s_nop 0
	s_nop 0
	s_nop 0
	s_nop 0
	s_nop 0
	s_nop 0
	s_nop 0
	s_nop 0
	s_nop 0
	s_nop 0
	s_nop 0
	s_nop 0
	s_nop 0
	s_nop 0
	s_nop 0
	s_nop 0
	s_nop 0
	s_nop 0
	s_nop 0
	s_nop 0
	s_nop 0
	s_nop 0
	s_nop 0
	s_nop 0
	s_nop 0
	s_nop 0
	s_nop 0
	s_nop 0
	s_nop 0
	s_nop 0
	s_nop 0
	s_nop 0
	s_nop 0
	s_nop 0
	s_nop 0
	s_nop 0
	s_nop 0
	s_nop 0
	s_nop 0
	s_nop 0
	s_nop 0
	s_nop 0
	s_nop 0
	s_nop 0
	s_nop 0
	s_nop 0
	s_nop 0
	s_nop 0
	s_nop 0
	s_nop 0
	s_nop 0
	s_nop 0
	s_nop 0
	s_nop 0
	s_nop 0
	s_nop 0
	s_nop 0
	s_nop 0
	s_nop 0
	s_nop 0
	s_nop 0
	s_nop 0
	s_nop 0
	s_nop 0
	s_nop 0
	s_nop 0
	s_nop 0
	s_nop 0
	s_nop 0
	s_nop 0
	s_nop 0
	s_nop 0
	s_nop 0
	s_nop 0
	s_nop 0
	s_nop 0
	s_nop 0
	s_nop 0
	s_nop 0
	s_nop 0
	s_nop 0
	s_nop 0
	s_nop 0
	s_nop 0
	s_nop 0
	s_nop 0
	s_nop 0
	s_nop 0
	s_nop 0
	s_nop 0
	s_nop 0
	s_nop 0
	s_nop 0
	s_nop 0
	s_nop 0
	s_nop 0
	s_nop 0
	s_nop 0
	s_nop 0
	s_nop 0
	s_nop 0
	s_nop 0
	s_nop 0
	s_nop 0
	s_nop 0
	s_nop 0
	s_nop 0
	s_nop 0
	s_nop 0
	s_nop 0
	s_nop 0
	s_nop 0
	s_nop 0
	s_nop 0
	s_nop 0
	s_nop 0
	s_nop 0
	s_nop 0
	s_nop 0
	s_nop 0
	s_nop 0
	s_nop 0
	s_nop 0
	s_nop 0
	s_nop 0
	s_nop 0
	s_nop 0
	s_nop 0
	s_nop 0
	s_nop 0
	s_nop 0
	s_nop 0
	s_nop 0
	s_nop 0
	s_nop 0
	s_nop 0
	s_nop 0
	s_nop 0
	s_nop 0
	s_nop 0
	s_nop 0
	s_nop 0
	s_nop 0
	s_nop 0
	s_nop 0
	s_nop 0
	s_nop 0
	s_nop 0
	s_nop 0
	s_nop 0
	s_nop 0
	s_nop 0
	s_nop 0
	s_nop 0
	s_nop 0
	s_nop 0
	s_nop 0
	s_nop 0
	s_nop 0
	s_nop 0
	s_nop 0
	s_nop 0
	s_nop 0
	s_nop 0
	s_nop 0
	s_nop 0
	s_nop 0
	s_nop 0
	s_nop 0
	s_nop 0
	s_nop 0
	s_nop 0
	s_nop 0
	s_nop 0
	s_nop 0
	s_nop 0
	s_nop 0
	s_nop 0
	s_nop 0
	s_nop 0
	s_nop 0
	s_nop 0
	s_nop 0
	s_nop 0
	s_nop 0
	s_nop 0
	s_nop 0
	s_nop 0
	s_nop 0
	s_nop 0
	s_nop 0
	s_nop 0
	s_nop 0
	s_nop 0
	s_nop 0
	s_nop 0
	s_nop 0
	s_nop 0
	s_nop 0
	s_nop 0
	s_nop 0
	s_nop 0
	s_nop 0
	s_nop 0
	s_nop 0
	s_nop 0
	s_nop 0
	s_nop 0
	s_nop 0
	s_nop 0
	s_nop 0
	s_nop 0
	s_nop 0
	s_nop 0
	s_nop 0
	s_nop 0
	s_nop 0
	s_nop 0
	s_nop 0
	s_nop 0
	s_nop 0
	s_nop 0
	s_nop 0
	s_nop 0
	s_nop 0
	s_nop 0
	s_nop 0
	s_nop 0
	s_nop 0
	s_nop 0
	s_nop 0
	s_nop 0
	s_nop 0
	s_nop 0
	s_nop 0
	s_nop 0
	s_nop 0
	s_nop 0
	s_nop 0
	s_nop 0
	s_nop 0
	s_nop 0
	s_nop 0
	s_nop 0
	s_nop 0
	s_nop 0
	s_nop 0
	s_nop 0
	s_nop 0
	s_nop 0
	s_nop 0
	s_nop 0
	s_nop 0
	s_nop 0
	s_nop 0
	s_nop 0
	s_nop 0
	s_nop 0
	s_nop 0
	s_nop 0
	s_nop 0
	s_nop 0
	s_nop 0
	s_nop 0
	s_nop 0
	s_nop 0
	s_nop 0
	s_nop 0
	s_nop 0
	s_nop 0
	s_nop 0
	s_nop 0
	s_nop 0
	s_nop 0
	s_nop 0
	s_nop 0
	s_nop 0
	s_nop 0
	s_nop 0
	s_nop 0
	s_nop 0
	s_nop 0
	s_nop 0
	s_nop 0
	s_nop 0
	s_nop 0
	s_nop 0
	s_nop 0
	s_nop 0
	s_nop 0
	s_nop 0
	s_nop 0
	s_nop 0
	s_nop 0
	s_nop 0
	s_nop 0
	s_nop 0
	s_nop 0
	s_nop 0
	s_nop 0
	s_nop 0
	s_nop 0
	s_nop 0
	s_nop 0
	s_nop 0
	s_nop 0
	s_nop 0
	s_nop 0
	s_nop 0
	s_nop 0
	s_nop 0
	s_nop 0
	s_nop 0
	s_nop 0
	s_nop 0
	s_nop 0
	s_nop 0
	s_nop 0
	s_nop 0
	s_nop 0
	s_nop 0
	s_nop 0
	s_nop 0
	s_nop 0
	s_nop 0
	s_nop 0
	s_nop 0
	s_nop 0
	s_nop 0
	s_nop 0
	s_nop 0
	s_nop 0
	s_nop 0
	s_nop 0
	s_nop 0
	s_nop 0
	s_nop 0
	s_nop 0
	s_nop 0
	s_nop 0
	s_nop 0
	s_nop 0
	s_nop 0
	s_nop 0
	s_nop 0
	s_nop 0
	s_nop 0
	s_nop 0
	s_nop 0
	s_nop 0
	s_nop 0
	s_nop 0
	s_nop 0
	s_nop 0
	s_nop 0
	s_nop 0
	s_nop 0
	s_nop 0
	s_nop 0
	s_nop 0
	s_nop 0
	s_nop 0
	s_nop 0
	s_nop 0
	s_nop 0
	s_nop 0
	s_nop 0
	s_nop 0
	s_nop 0
	s_nop 0
	s_nop 0
	s_nop 0
	s_nop 0
	s_nop 0
	s_nop 0
	s_nop 0
	s_nop 0
	s_nop 0
	s_nop 0
	s_nop 0
	s_nop 0
	s_nop 0
	s_nop 0
	s_nop 0
	s_nop 0

; __global__ void __launch_bounds__(NWAVES * 64, 2) mk_fwd(Args args) {
;     ...
;                     if (diff) {
;                         asm volatile("s_waitcnt vmcnt(0)" ::: "memory");
;                         __builtin_amdgcn_fence(__ATOMIC_ACQUIRE, "agent");
;                         const int r = wave * 32 + (lane >> 1), c0 = (lane & 1) * 64;
;                         const bf16* s1 = scrg + r * 256 + c0; const bf16* s2 = s1 + 128;
;                         float ss = 0.f;
; #pragma unroll
;                         for (int c = 0; c < 8; ++c) { const v4u a = *(const volatile v4u*)(s1 + 8 * c), bq = *(const volatile v4u*)(s2 + 8 * c);
; #pragma unroll
;                             for (int e = 0; e < 4; ++e) { const float d0 = __uint_as_float(a[e] << 16) - lam * __uint_as_float(bq[e] << 16), d1 = __uint_as_float(a[e] & 0xffff0000u) - lam * __uint_as_float(bq[e] & 0xffff0000u); ss += d0 * d0 + d1 * d1; } }
;                         ss += __shfl_xor(ss, 1);
;                         const float rn = __builtin_amdgcn_rsqf(ss * (1.0f / 128.0f) + 1e-5f) * oml;
;                         bf16* mo = MIX + (size_t)(rowbase + q0 + r) * DM + 512 + h * 128 + c0;
; #pragma unroll
;                         for (int c = 0; c < 8; ++c) { const v4u a = *(const volatile v4u*)(s1 + 8 * c), bq = *(const volatile v4u*)(s2 + 8 * c);
;                             const f32x4 g0 = *(const f32x4*)(gsub + c0 + 8 * c), g1 = *(const f32x4*)(gsub + c0 + 8 * c + 4); v4u o;
.LBB0_917:
	s_and_b64 vcc, exec, s[4:5]
	s_cbranch_vccnz .LBB0_822
	s_waitcnt vmcnt(0)
	s_waitcnt vmcnt(0)
	s_nop 0
	global_load_dwordx4 v[60:63], v[216:217], off sc0 sc1
	global_load_dwordx4 v[64:67], v[216:217], off offset:256 sc0 sc1
	global_load_dwordx4 v[68:71], v[216:217], off offset:16 sc0 sc1
	global_load_dwordx4 v[72:75], v[216:217], off offset:272 sc0 sc1
	global_load_dwordx4 v[76:79], v[216:217], off offset:32 sc0 sc1
	global_load_dwordx4 v[80:83], v[216:217], off offset:288 sc0 sc1
	global_load_dwordx4 v[84:87], v[216:217], off offset:48 sc0 sc1
	global_load_dwordx4 v[88:91], v[216:217], off offset:304 sc0 sc1
	global_load_dwordx4 v[92:95], v[216:217], off offset:64 sc0 sc1
	global_load_dwordx4 v[96:99], v[216:217], off offset:320 sc0 sc1
	global_load_dwordx4 v[100:103], v[216:217], off offset:80 sc0 sc1
	global_load_dwordx4 v[104:107], v[216:217], off offset:336 sc0 sc1
	global_load_dwordx4 v[108:111], v[216:217], off offset:96 sc0 sc1
	global_load_dwordx4 v[112:115], v[216:217], off offset:352 sc0 sc1
	global_load_dwordx4 v[116:119], v[216:217], off offset:112 sc0 sc1
	global_load_dwordx4 v[120:123], v[216:217], off offset:368 sc0 sc1
	global_load_dwordx4 v[124:127], v[220:221], off offset:512
	global_load_dwordx4 v[128:131], v[220:221], off offset:528
	global_load_dwordx4 v[132:135], v[220:221], off offset:544
	global_load_dwordx4 v[136:139], v[220:221], off offset:560
	global_load_dwordx4 v[140:143], v[220:221], off offset:576
	global_load_dwordx4 v[144:147], v[220:221], off offset:592
	global_load_dwordx4 v[148:151], v[220:221], off offset:608
	global_load_dwordx4 v[152:155], v[220:221], off offset:624
	global_load_dwordx4 v[156:159], v[220:221], off offset:640
	global_load_dwordx4 v[160:163], v[220:221], off offset:656
	global_load_dwordx4 v[164:167], v[220:221], off offset:672
	global_load_dwordx4 v[168:171], v[220:221], off offset:688
	global_load_dwordx4 v[172:175], v[220:221], off offset:704
	global_load_dwordx4 v[176:179], v[220:221], off offset:720
	global_load_dwordx4 v[180:183], v[220:221], off offset:736
	global_load_dwordx4 v[184:187], v[220:221], off offset:752
	s_lshl_b32 s8, s83, 8
	v_mov_b32_e32 v223, v1
	v_add_u32_e32 v2, s64, v236
	v_ashrrev_i32_e32 v3, 31, v2
	v_lshlrev_b64 v[2:3], 11, v[2:3]
	v_lshl_add_u64 v[2:3], s[36:37], 0, v[2:3]
	v_lshl_add_u64 v[2:3], v[2:3], 0, s[8:9]
	v_lshl_add_u64 v[2:3], v[2:3], 0, v[222:223]
	v_mov_b32_e32 v12, 0
	v_mov_b32_e32 v13, 0
	v_mov_b32_e32 v14, 0
	v_mov_b32_e32 v15, 0
	s_waitcnt vmcnt(30)
	v_lshlrev_b32_e32 v4, 16, v60
	v_lshlrev_b32_e32 v5, 16, v64
	v_and_b32_e32 v60, s80, v60
	v_and_b32_e32 v64, s80, v64
	v_fma_f32 v60, -v218, v64, v60
	v_fma_f32 v64, -v218, v5, v4
	v_fmac_f32_e32 v12, v60, v60
	v_fmac_f32_e32 v12, v64, v64
	v_lshlrev_b32_e32 v6, 16, v61
	v_lshlrev_b32_e32 v7, 16, v65
	v_and_b32_e32 v61, s80, v61
	v_and_b32_e32 v65, s80, v65
	v_fma_f32 v61, -v218, v65, v61
	v_fma_f32 v65, -v218, v7, v6
	v_fmac_f32_e32 v13, v61, v61
	v_fmac_f32_e32 v13, v65, v65
	v_lshlrev_b32_e32 v8, 16, v62
	v_lshlrev_b32_e32 v9, 16, v66
	v_and_b32_e32 v62, s80, v62
	v_and_b32_e32 v66, s80, v66
	v_fma_f32 v62, -v218, v66, v62
	v_fma_f32 v66, -v218, v9, v8
	v_fmac_f32_e32 v14, v62, v62
	v_fmac_f32_e32 v14, v66, v66
	v_lshlrev_b32_e32 v10, 16, v63
	v_lshlrev_b32_e32 v11, 16, v67
	v_and_b32_e32 v63, s80, v63
	v_and_b32_e32 v67, s80, v67
	v_fma_f32 v63, -v218, v67, v63
	v_fma_f32 v67, -v218, v11, v10
	v_fmac_f32_e32 v15, v63, v63
	v_fmac_f32_e32 v15, v67, v67
	s_waitcnt vmcnt(28)
	v_lshlrev_b32_e32 v4, 16, v68
	v_lshlrev_b32_e32 v5, 16, v72
	v_and_b32_e32 v68, s80, v68
	v_and_b32_e32 v72, s80, v72
	v_fma_f32 v68, -v218, v72, v68
	v_fma_f32 v72, -v218, v5, v4
	v_fmac_f32_e32 v12, v68, v68
	v_fmac_f32_e32 v12, v72, v72
	v_lshlrev_b32_e32 v6, 16, v69
	v_lshlrev_b32_e32 v7, 16, v73
	v_and_b32_e32 v69, s80, v69
	v_and_b32_e32 v73, s80, v73
	v_fma_f32 v69, -v218, v73, v69
	v_fma_f32 v73, -v218, v7, v6
	v_fmac_f32_e32 v13, v69, v69
	v_fmac_f32_e32 v13, v73, v73
	v_lshlrev_b32_e32 v8, 16, v70
	v_lshlrev_b32_e32 v9, 16, v74
	v_and_b32_e32 v70, s80, v70
	v_and_b32_e32 v74, s80, v74
	v_fma_f32 v70, -v218, v74, v70
	v_fma_f32 v74, -v218, v9, v8
	v_fmac_f32_e32 v14, v70, v70
	v_fmac_f32_e32 v14, v74, v74
	v_lshlrev_b32_e32 v10, 16, v71
	v_lshlrev_b32_e32 v11, 16, v75
	v_and_b32_e32 v71, s80, v71
	v_and_b32_e32 v75, s80, v75
	v_fma_f32 v71, -v218, v75, v71
	v_fma_f32 v75, -v218, v11, v10
	v_fmac_f32_e32 v15, v71, v71
	v_fmac_f32_e32 v15, v75, v75
	s_waitcnt vmcnt(26)
	v_lshlrev_b32_e32 v4, 16, v76
	v_lshlrev_b32_e32 v5, 16, v80
	v_and_b32_e32 v76, s80, v76
	v_and_b32_e32 v80, s80, v80
	v_fma_f32 v76, -v218, v80, v76
	v_fma_f32 v80, -v218, v5, v4
	v_fmac_f32_e32 v12, v76, v76
	v_fmac_f32_e32 v12, v80, v80
	v_lshlrev_b32_e32 v6, 16, v77
	v_lshlrev_b32_e32 v7, 16, v81
	v_and_b32_e32 v77, s80, v77
	v_and_b32_e32 v81, s80, v81
	v_fma_f32 v77, -v218, v81, v77
	v_fma_f32 v81, -v218, v7, v6
	v_fmac_f32_e32 v13, v77, v77
	v_fmac_f32_e32 v13, v81, v81
	v_lshlrev_b32_e32 v8, 16, v78
	v_lshlrev_b32_e32 v9, 16, v82
	v_and_b32_e32 v78, s80, v78
	v_and_b32_e32 v82, s80, v82
	v_fma_f32 v78, -v218, v82, v78
	v_fma_f32 v82, -v218, v9, v8
	v_fmac_f32_e32 v14, v78, v78
	v_fmac_f32_e32 v14, v82, v82
	v_lshlrev_b32_e32 v10, 16, v79
	v_lshlrev_b32_e32 v11, 16, v83
	v_and_b32_e32 v79, s80, v79
	v_and_b32_e32 v83, s80, v83
	v_fma_f32 v79, -v218, v83, v79
	v_fma_f32 v83, -v218, v11, v10
	v_fmac_f32_e32 v15, v79, v79
	v_fmac_f32_e32 v15, v83, v83
	s_waitcnt vmcnt(24)
; __global__ void __launch_bounds__(NWAVES * 64, 2) mk_fwd(Args args) {
;     ...
;                         for (int c = 0; c < 8; ++c) { const v4u a = *(const volatile v4u*)(s1 + 8 * c), bq = *(const volatile v4u*)(s2 + 8 * c);
; #pragma unroll
;                             for (int e = 0; e < 4; ++e) { const float d0 = __uint_as_float(a[e] << 16) - lam * __uint_as_float(bq[e] << 16), d1 = __uint_as_float(a[e] & 0xffff0000u) - lam * __uint_as_float(bq[e] & 0xffff0000u); ss += d0 * d0 + d1 * d1; } }
;                         ss += __shfl_xor(ss, 1);
;                         const float rn = __builtin_amdgcn_rsqf(ss * (1.0f / 128.0f) + 1e-5f) * oml;
	v_lshlrev_b32_e32 v4, 16, v84
	v_lshlrev_b32_e32 v5, 16, v88
	v_and_b32_e32 v84, s80, v84
	v_and_b32_e32 v88, s80, v88
	v_fma_f32 v84, -v218, v88, v84
	v_fma_f32 v88, -v218, v5, v4
	v_fmac_f32_e32 v12, v84, v84
	v_fmac_f32_e32 v12, v88, v88
	v_lshlrev_b32_e32 v6, 16, v85
	v_lshlrev_b32_e32 v7, 16, v89
	v_and_b32_e32 v85, s80, v85
	v_and_b32_e32 v89, s80, v89
	v_fma_f32 v85, -v218, v89, v85
	v_fma_f32 v89, -v218, v7, v6
	v_fmac_f32_e32 v13, v85, v85
	v_fmac_f32_e32 v13, v89, v89
	v_lshlrev_b32_e32 v8, 16, v86
	v_lshlrev_b32_e32 v9, 16, v90
	v_and_b32_e32 v86, s80, v86
	v_and_b32_e32 v90, s80, v90
	v_fma_f32 v86, -v218, v90, v86
	v_fma_f32 v90, -v218, v9, v8
	v_fmac_f32_e32 v14, v86, v86
	v_fmac_f32_e32 v14, v90, v90
	v_lshlrev_b32_e32 v10, 16, v87
	v_lshlrev_b32_e32 v11, 16, v91
	v_and_b32_e32 v87, s80, v87
	v_and_b32_e32 v91, s80, v91
	v_fma_f32 v87, -v218, v91, v87
	v_fma_f32 v91, -v218, v11, v10
	v_fmac_f32_e32 v15, v87, v87
	v_fmac_f32_e32 v15, v91, v91
	s_waitcnt vmcnt(22)
	v_lshlrev_b32_e32 v4, 16, v92
	v_lshlrev_b32_e32 v5, 16, v96
	v_and_b32_e32 v92, s80, v92
	v_and_b32_e32 v96, s80, v96
	v_fma_f32 v92, -v218, v96, v92
	v_fma_f32 v96, -v218, v5, v4
	v_fmac_f32_e32 v12, v92, v92
	v_fmac_f32_e32 v12, v96, v96
	v_lshlrev_b32_e32 v6, 16, v93
	v_lshlrev_b32_e32 v7, 16, v97
	v_and_b32_e32 v93, s80, v93
	v_and_b32_e32 v97, s80, v97
	v_fma_f32 v93, -v218, v97, v93
	v_fma_f32 v97, -v218, v7, v6
	v_fmac_f32_e32 v13, v93, v93
	v_fmac_f32_e32 v13, v97, v97
	v_lshlrev_b32_e32 v8, 16, v94
	v_lshlrev_b32_e32 v9, 16, v98
	v_and_b32_e32 v94, s80, v94
	v_and_b32_e32 v98, s80, v98
	v_fma_f32 v94, -v218, v98, v94
	v_fma_f32 v98, -v218, v9, v8
	v_fmac_f32_e32 v14, v94, v94
	v_fmac_f32_e32 v14, v98, v98
	v_lshlrev_b32_e32 v10, 16, v95
	v_lshlrev_b32_e32 v11, 16, v99
	v_and_b32_e32 v95, s80, v95
	v_and_b32_e32 v99, s80, v99
	v_fma_f32 v95, -v218, v99, v95
	v_fma_f32 v99, -v218, v11, v10
	v_fmac_f32_e32 v15, v95, v95
	v_fmac_f32_e32 v15, v99, v99
	s_waitcnt vmcnt(20)
	v_lshlrev_b32_e32 v4, 16, v100
	v_lshlrev_b32_e32 v5, 16, v104
	v_and_b32_e32 v100, s80, v100
	v_and_b32_e32 v104, s80, v104
	v_fma_f32 v100, -v218, v104, v100
	v_fma_f32 v104, -v218, v5, v4
	v_fmac_f32_e32 v12, v100, v100
	v_fmac_f32_e32 v12, v104, v104
	v_lshlrev_b32_e32 v6, 16, v101
	v_lshlrev_b32_e32 v7, 16, v105
	v_and_b32_e32 v101, s80, v101
	v_and_b32_e32 v105, s80, v105
	v_fma_f32 v101, -v218, v105, v101
	v_fma_f32 v105, -v218, v7, v6
	v_fmac_f32_e32 v13, v101, v101
	v_fmac_f32_e32 v13, v105, v105
	v_lshlrev_b32_e32 v8, 16, v102
	v_lshlrev_b32_e32 v9, 16, v106
	v_and_b32_e32 v102, s80, v102
	v_and_b32_e32 v106, s80, v106
	v_fma_f32 v102, -v218, v106, v102
	v_fma_f32 v106, -v218, v9, v8
	v_fmac_f32_e32 v14, v102, v102
	v_fmac_f32_e32 v14, v106, v106
	v_lshlrev_b32_e32 v10, 16, v103
	v_lshlrev_b32_e32 v11, 16, v107
	v_and_b32_e32 v103, s80, v103
	v_and_b32_e32 v107, s80, v107
	v_fma_f32 v103, -v218, v107, v103
	v_fma_f32 v107, -v218, v11, v10
	v_fmac_f32_e32 v15, v103, v103
	v_fmac_f32_e32 v15, v107, v107
	s_waitcnt vmcnt(18)
	v_lshlrev_b32_e32 v4, 16, v108
	v_lshlrev_b32_e32 v5, 16, v112
	v_and_b32_e32 v108, s80, v108
	v_and_b32_e32 v112, s80, v112
	v_fma_f32 v108, -v218, v112, v108
	v_fma_f32 v112, -v218, v5, v4
	v_fmac_f32_e32 v12, v108, v108
	v_fmac_f32_e32 v12, v112, v112
	v_lshlrev_b32_e32 v6, 16, v109
	v_lshlrev_b32_e32 v7, 16, v113
	v_and_b32_e32 v109, s80, v109
	v_and_b32_e32 v113, s80, v113
	v_fma_f32 v109, -v218, v113, v109
	v_fma_f32 v113, -v218, v7, v6
	v_fmac_f32_e32 v13, v109, v109
	v_fmac_f32_e32 v13, v113, v113
	v_lshlrev_b32_e32 v8, 16, v110
	v_lshlrev_b32_e32 v9, 16, v114
	v_and_b32_e32 v110, s80, v110
	v_and_b32_e32 v114, s80, v114
	v_fma_f32 v110, -v218, v114, v110
	v_fma_f32 v114, -v218, v9, v8
	v_fmac_f32_e32 v14, v110, v110
	v_fmac_f32_e32 v14, v114, v114
	v_lshlrev_b32_e32 v10, 16, v111
	v_lshlrev_b32_e32 v11, 16, v115
	v_and_b32_e32 v111, s80, v111
	v_and_b32_e32 v115, s80, v115
	v_fma_f32 v111, -v218, v115, v111
	v_fma_f32 v115, -v218, v11, v10
	v_fmac_f32_e32 v15, v111, v111
	v_fmac_f32_e32 v15, v115, v115
	s_waitcnt vmcnt(16)
	v_lshlrev_b32_e32 v4, 16, v116
	v_lshlrev_b32_e32 v5, 16, v120
	v_and_b32_e32 v116, s80, v116
	v_and_b32_e32 v120, s80, v120
	v_fma_f32 v116, -v218, v120, v116
	v_fma_f32 v120, -v218, v5, v4
	v_fmac_f32_e32 v12, v116, v116
	v_fmac_f32_e32 v12, v120, v120
	v_lshlrev_b32_e32 v6, 16, v117
	v_lshlrev_b32_e32 v7, 16, v121
	v_and_b32_e32 v117, s80, v117
	v_and_b32_e32 v121, s80, v121
	v_fma_f32 v117, -v218, v121, v117
	v_fma_f32 v121, -v218, v7, v6
	v_fmac_f32_e32 v13, v117, v117
	v_fmac_f32_e32 v13, v121, v121
	v_lshlrev_b32_e32 v8, 16, v118
	v_lshlrev_b32_e32 v9, 16, v122
	v_and_b32_e32 v118, s80, v118
	v_and_b32_e32 v122, s80, v122
	v_fma_f32 v118, -v218, v122, v118
	v_fma_f32 v122, -v218, v9, v8
	v_fmac_f32_e32 v14, v118, v118
	v_fmac_f32_e32 v14, v122, v122
	v_lshlrev_b32_e32 v10, 16, v119
	v_lshlrev_b32_e32 v11, 16, v123
	v_and_b32_e32 v119, s80, v119
	v_and_b32_e32 v123, s80, v123
	v_fma_f32 v119, -v218, v123, v119
	v_fma_f32 v123, -v218, v11, v10
	v_fmac_f32_e32 v15, v119, v119
	v_fmac_f32_e32 v15, v123, v123
	v_add_f32_e32 v12, v12, v13
	v_add_f32_e32 v14, v14, v15
	v_add_f32_e32 v0, v12, v14
	s_nop 0
	ds_bpermute_b32 v4, v237, v0
	s_waitcnt lgkmcnt(0)
	v_add_f32_e32 v0, v0, v4
	v_fmamk_f32 v0, v0, 0x3c000000, v239
	v_rsq_f32_e32 v0, v0
	s_nop 1
	v_mul_f32_e32 v0, 0x3f24fd5c, v0
	s_waitcnt vmcnt(0)
; __device__ __forceinline__ unsigned pk2(float lo, float hi) { return f2bf(lo) | (f2bf(hi) << 16); }
; __global__ void __launch_bounds__(NWAVES * 64, 2) mk_fwd(Args args) {
;     ...
;                         bf16* mo = MIX + (size_t)(rowbase + q0 + r) * DM + 512 + h * 128 + c0;
; #pragma unroll
;                         for (int c = 0; c < 8; ++c) { const v4u a = *(const volatile v4u*)(s1 + 8 * c), bq = *(const volatile v4u*)(s2 + 8 * c);
;                             const f32x4 g0 = *(const f32x4*)(gsub + c0 + 8 * c), g1 = *(const f32x4*)(gsub + c0 + 8 * c + 4); v4u o;
; #pragma unroll
;                             for (int e = 0; e < 4; ++e) { const float d0 = __uint_as_float(a[e] << 16) - lam * __uint_as_float(bq[e] << 16), d1 = __uint_as_float(a[e] & 0xffff0000u) - lam * __uint_as_float(bq[e] & 0xffff0000u);
;                                 const float ga = (e < 2) ? g0[2 * e] : g1[2 * e - 4], gb = (e < 2) ? g0[2 * e + 1] : g1[2 * e - 3];
;                                 o[e] = pk2(d0 * rn * ga, d1 * rn * gb); }
;                             *(v4u*)(mo + 8 * c) = o; }
;                         asm volatile("s_waitcnt vmcnt(0)" ::: "memory");
;                         __syncthreads();
	v_mul_f32_e32 v64, v0, v64
	v_mul_f32_e32 v60, v0, v60
	v_mul_f32_e32 v64, v64, v124
	v_mul_f32_e32 v60, v60, v125
	v_cvt_pk_bf16_f32 v4, v64, v60
	v_mul_f32_e32 v65, v0, v65
	v_mul_f32_e32 v61, v0, v61
	v_mul_f32_e32 v65, v65, v126
	v_mul_f32_e32 v61, v61, v127
	v_cvt_pk_bf16_f32 v5, v65, v61
	v_mul_f32_e32 v66, v0, v66
	v_mul_f32_e32 v62, v0, v62
	v_mul_f32_e32 v66, v66, v128
	v_mul_f32_e32 v62, v62, v129
	v_cvt_pk_bf16_f32 v6, v66, v62
	v_mul_f32_e32 v67, v0, v67
	v_mul_f32_e32 v63, v0, v63
	v_mul_f32_e32 v67, v67, v130
	v_mul_f32_e32 v63, v63, v131
	v_cvt_pk_bf16_f32 v7, v67, v63
	global_store_dwordx4 v[2:3], v[4:7], off offset:1024
	v_mul_f32_e32 v72, v0, v72
	v_mul_f32_e32 v68, v0, v68
	v_mul_f32_e32 v72, v72, v132
	v_mul_f32_e32 v68, v68, v133
	v_cvt_pk_bf16_f32 v8, v72, v68
	v_mul_f32_e32 v73, v0, v73
	v_mul_f32_e32 v69, v0, v69
	v_mul_f32_e32 v73, v73, v134
	v_mul_f32_e32 v69, v69, v135
	v_cvt_pk_bf16_f32 v9, v73, v69
	v_mul_f32_e32 v74, v0, v74
	v_mul_f32_e32 v70, v0, v70
	v_mul_f32_e32 v74, v74, v136
	v_mul_f32_e32 v70, v70, v137
	v_cvt_pk_bf16_f32 v10, v74, v70
	v_mul_f32_e32 v75, v0, v75
	v_mul_f32_e32 v71, v0, v71
	v_mul_f32_e32 v75, v75, v138
	v_mul_f32_e32 v71, v71, v139
	v_cvt_pk_bf16_f32 v11, v75, v71
	global_store_dwordx4 v[2:3], v[8:11], off offset:1040
	v_mul_f32_e32 v80, v0, v80
	v_mul_f32_e32 v76, v0, v76
	v_mul_f32_e32 v80, v80, v140
	v_mul_f32_e32 v76, v76, v141
	v_cvt_pk_bf16_f32 v4, v80, v76
	v_mul_f32_e32 v81, v0, v81
	v_mul_f32_e32 v77, v0, v77
	v_mul_f32_e32 v81, v81, v142
	v_mul_f32_e32 v77, v77, v143
	v_cvt_pk_bf16_f32 v5, v81, v77
	v_mul_f32_e32 v82, v0, v82
	v_mul_f32_e32 v78, v0, v78
	v_mul_f32_e32 v82, v82, v144
	v_mul_f32_e32 v78, v78, v145
	v_cvt_pk_bf16_f32 v6, v82, v78
	v_mul_f32_e32 v83, v0, v83
	v_mul_f32_e32 v79, v0, v79
	v_mul_f32_e32 v83, v83, v146
	v_mul_f32_e32 v79, v79, v147
	v_cvt_pk_bf16_f32 v7, v83, v79
	global_store_dwordx4 v[2:3], v[4:7], off offset:1056
	v_mul_f32_e32 v88, v0, v88
	v_mul_f32_e32 v84, v0, v84
	v_mul_f32_e32 v88, v88, v148
	v_mul_f32_e32 v84, v84, v149
	v_cvt_pk_bf16_f32 v8, v88, v84
	v_mul_f32_e32 v89, v0, v89
	v_mul_f32_e32 v85, v0, v85
	v_mul_f32_e32 v89, v89, v150
	v_mul_f32_e32 v85, v85, v151
	v_cvt_pk_bf16_f32 v9, v89, v85
	v_mul_f32_e32 v90, v0, v90
	v_mul_f32_e32 v86, v0, v86
	v_mul_f32_e32 v90, v90, v152
	v_mul_f32_e32 v86, v86, v153
	v_cvt_pk_bf16_f32 v10, v90, v86
	v_mul_f32_e32 v91, v0, v91
	v_mul_f32_e32 v87, v0, v87
	v_mul_f32_e32 v91, v91, v154
	v_mul_f32_e32 v87, v87, v155
	v_cvt_pk_bf16_f32 v11, v91, v87
	global_store_dwordx4 v[2:3], v[8:11], off offset:1072
	v_mul_f32_e32 v96, v0, v96
	v_mul_f32_e32 v92, v0, v92
	v_mul_f32_e32 v96, v96, v156
	v_mul_f32_e32 v92, v92, v157
	v_cvt_pk_bf16_f32 v4, v96, v92
	v_mul_f32_e32 v97, v0, v97
	v_mul_f32_e32 v93, v0, v93
	v_mul_f32_e32 v97, v97, v158
	v_mul_f32_e32 v93, v93, v159
	v_cvt_pk_bf16_f32 v5, v97, v93
	v_mul_f32_e32 v98, v0, v98
	v_mul_f32_e32 v94, v0, v94
	v_mul_f32_e32 v98, v98, v160
	v_mul_f32_e32 v94, v94, v161
	v_cvt_pk_bf16_f32 v6, v98, v94
	v_mul_f32_e32 v99, v0, v99
	v_mul_f32_e32 v95, v0, v95
	v_mul_f32_e32 v99, v99, v162
	v_mul_f32_e32 v95, v95, v163
	v_cvt_pk_bf16_f32 v7, v99, v95
	global_store_dwordx4 v[2:3], v[4:7], off offset:1088
	v_mul_f32_e32 v104, v0, v104
	v_mul_f32_e32 v100, v0, v100
	v_mul_f32_e32 v104, v104, v164
	v_mul_f32_e32 v100, v100, v165
	v_cvt_pk_bf16_f32 v8, v104, v100
	v_mul_f32_e32 v105, v0, v105
	v_mul_f32_e32 v101, v0, v101
	v_mul_f32_e32 v105, v105, v166
	v_mul_f32_e32 v101, v101, v167
	v_cvt_pk_bf16_f32 v9, v105, v101
	v_mul_f32_e32 v106, v0, v106
	v_mul_f32_e32 v102, v0, v102
	v_mul_f32_e32 v106, v106, v168
	v_mul_f32_e32 v102, v102, v169
	v_cvt_pk_bf16_f32 v10, v106, v102
	v_mul_f32_e32 v107, v0, v107
	v_mul_f32_e32 v103, v0, v103
	v_mul_f32_e32 v107, v107, v170
	v_mul_f32_e32 v103, v103, v171
	v_cvt_pk_bf16_f32 v11, v107, v103
	global_store_dwordx4 v[2:3], v[8:11], off offset:1104
	v_mul_f32_e32 v112, v0, v112
	v_mul_f32_e32 v108, v0, v108
	v_mul_f32_e32 v112, v112, v172
	v_mul_f32_e32 v108, v108, v173
	v_cvt_pk_bf16_f32 v4, v112, v108
	v_mul_f32_e32 v113, v0, v113
	v_mul_f32_e32 v109, v0, v109
	v_mul_f32_e32 v113, v113, v174
	v_mul_f32_e32 v109, v109, v175
	v_cvt_pk_bf16_f32 v5, v113, v109
	v_mul_f32_e32 v114, v0, v114
	v_mul_f32_e32 v110, v0, v110
	v_mul_f32_e32 v114, v114, v176
	v_mul_f32_e32 v110, v110, v177
	v_cvt_pk_bf16_f32 v6, v114, v110
	v_mul_f32_e32 v115, v0, v115
	v_mul_f32_e32 v111, v0, v111
	v_mul_f32_e32 v115, v115, v178
	v_mul_f32_e32 v111, v111, v179
	v_cvt_pk_bf16_f32 v7, v115, v111
	global_store_dwordx4 v[2:3], v[4:7], off offset:1120
	v_mul_f32_e32 v120, v0, v120
	v_mul_f32_e32 v116, v0, v116
	v_mul_f32_e32 v120, v120, v180
	v_mul_f32_e32 v116, v116, v181
	v_cvt_pk_bf16_f32 v8, v120, v116
	v_mul_f32_e32 v121, v0, v121
	v_mul_f32_e32 v117, v0, v117
	v_mul_f32_e32 v121, v121, v182
	v_mul_f32_e32 v117, v117, v183
	v_cvt_pk_bf16_f32 v9, v121, v117
	v_mul_f32_e32 v122, v0, v122
	v_mul_f32_e32 v118, v0, v118
	v_mul_f32_e32 v122, v122, v184
	v_mul_f32_e32 v118, v118, v185
	v_cvt_pk_bf16_f32 v10, v122, v118
	v_mul_f32_e32 v123, v0, v123
	v_mul_f32_e32 v119, v0, v119
	v_mul_f32_e32 v123, v123, v186
	v_mul_f32_e32 v119, v119, v187
	v_cvt_pk_bf16_f32 v11, v123, v119
	global_store_dwordx4 v[2:3], v[8:11], off offset:1136
	s_waitcnt vmcnt(0)
	s_barrier
	s_branch .LBB0_822
; __global__ void __launch_bounds__(NWAVES * 64, 2) mk_fwd(Args args) {
;     ...
;                         __syncthreads();
;                     }
;                 }
	s_nop 0
	s_nop 0
	s_nop 0
	s_nop 0
	s_nop 0
	s_nop 0
	s_nop 0
	s_nop 0
	s_nop 0
	s_nop 0
	s_nop 0
	s_nop 0
	s_nop 0
	s_nop 0
	s_nop 0
	s_nop 0
	s_nop 0
	s_nop 0
	s_nop 0
	s_nop 0
	s_nop 0
	s_nop 0
	s_nop 0
	s_nop 0
	s_nop 0
	s_nop 0
	s_nop 0
	s_nop 0
	s_nop 0
	s_nop 0
	s_nop 0
	s_nop 0
	s_nop 0
	s_nop 0
	s_nop 0
	s_nop 0
	s_nop 0
	s_nop 0
	s_nop 0
	s_nop 0
	s_nop 0
	s_nop 0
	s_nop 0
	s_nop 0
	s_nop 0
	s_nop 0
	s_nop 0
	s_nop 0
	s_nop 0
	s_nop 0
	s_nop 0
	s_nop 0
	s_nop 0
	s_nop 0
	s_nop 0
	s_nop 0
	s_nop 0
	s_nop 0
	s_nop 0
	s_nop 0
	s_nop 0
	s_nop 0
	s_nop 0
	s_nop 0
	s_nop 0
	s_nop 0
	s_nop 0
	s_nop 0
	s_nop 0
	s_nop 0
	s_nop 0
	s_nop 0
	s_nop 0
	s_nop 0
	s_nop 0
	s_nop 0
	s_nop 0
	s_nop 0
	s_nop 0
	s_nop 0
	s_nop 0
	s_nop 0
	s_nop 0
	s_nop 0
	s_nop 0
	s_nop 0
	s_nop 0
	s_nop 0
	s_nop 0
	s_nop 0
	s_nop 0
	s_nop 0
	s_nop 0
	s_nop 0
	s_nop 0
	s_nop 0
	s_nop 0
	s_nop 0
	s_nop 0
	s_nop 0
	s_nop 0
	s_nop 0
	s_nop 0
	s_nop 0
	s_nop 0
	s_nop 0
	s_nop 0
	s_nop 0
	s_nop 0
	s_nop 0
	s_nop 0
	s_nop 0
	s_nop 0
	s_nop 0
	s_nop 0
	s_nop 0
	s_nop 0
	s_nop 0
	s_nop 0
	s_nop 0
	s_nop 0
	s_nop 0
	s_nop 0
	s_nop 0
	s_nop 0
	s_nop 0
	s_nop 0
	s_nop 0
	s_nop 0
	s_nop 0
	s_nop 0
	s_nop 0
	s_nop 0
	s_nop 0
	s_nop 0
	s_nop 0
	s_nop 0
	s_nop 0
	s_nop 0
	s_nop 0
	s_nop 0
	s_nop 0
	s_nop 0
	s_nop 0
	s_nop 0
	s_nop 0
	s_nop 0
	s_nop 0
	s_nop 0
	s_nop 0
	s_nop 0
	s_nop 0
	s_nop 0
	s_nop 0
	s_nop 0
	s_nop 0
	s_nop 0
	s_nop 0
	s_nop 0
	s_nop 0
	s_nop 0
	s_nop 0
	s_nop 0
	s_nop 0
	s_nop 0
	s_nop 0
	s_nop 0
	s_nop 0
	s_nop 0
	s_nop 0
	s_nop 0
	s_nop 0
	s_nop 0
	s_nop 0
	s_nop 0
	s_nop 0
	s_nop 0
	s_nop 0
	s_nop 0
	s_nop 0
	s_nop 0
	s_nop 0
	s_nop 0
	s_nop 0
	s_nop 0
	s_nop 0
	s_nop 0
	s_nop 0
	s_nop 0
	s_nop 0
	s_nop 0
	s_nop 0
	s_nop 0
	s_nop 0
	s_nop 0
	s_nop 0
	s_nop 0
	s_nop 0
	s_nop 0
	s_nop 0
	s_nop 0
	s_nop 0
	s_nop 0
	s_nop 0
	s_nop 0
	s_nop 0
	s_nop 0
	s_nop 0
	s_nop 0
	s_nop 0
	s_nop 0
	s_nop 0
	s_nop 0
	s_nop 0
	s_nop 0
	s_nop 0
	s_nop 0
	s_nop 0
	s_nop 0
	s_nop 0
	s_nop 0
	s_nop 0
	s_nop 0
	s_nop 0
	s_nop 0
	s_nop 0
	s_nop 0
	s_nop 0
	s_nop 0
	s_nop 0
	s_nop 0
	s_nop 0
	s_nop 0
	s_nop 0
	s_nop 0
	s_nop 0
	s_nop 0
	s_nop 0
	s_nop 0
	s_nop 0
	s_nop 0
	s_nop 0
	s_nop 0
	s_nop 0
	s_nop 0
	s_nop 0
	s_nop 0
	s_nop 0
	s_nop 0
	s_nop 0
	s_nop 0
	s_nop 0
	s_nop 0
	s_nop 0
	s_nop 0
	s_nop 0
	s_nop 0
	s_nop 0
	s_nop 0
	s_nop 0
	s_nop 0
	s_nop 0
	s_nop 0
	s_nop 0
	s_nop 0
	s_nop 0
	s_nop 0
	s_nop 0
	s_nop 0
	s_nop 0
	s_nop 0
	s_nop 0
	s_nop 0
	s_nop 0
	s_nop 0
	s_nop 0
	s_nop 0
	s_nop 0
	s_nop 0
	s_nop 0
	s_nop 0
	s_nop 0
	s_nop 0
	s_nop 0
	s_nop 0
	s_nop 0
	s_nop 0
	s_nop 0
	s_nop 0
	s_nop 0
	s_nop 0
	s_nop 0
	s_nop 0
	s_nop 0
	s_nop 0
	s_nop 0
	s_nop 0
	s_nop 0
	s_nop 0
	s_nop 0
	s_nop 0
	s_nop 0
	s_nop 0
	s_nop 0
	s_nop 0
	s_nop 0
	s_nop 0
	s_nop 0
	s_nop 0
	s_nop 0
	s_nop 0
	s_nop 0
	s_nop 0
	s_nop 0
	s_nop 0
	s_nop 0
	s_nop 0
	s_nop 0
	s_nop 0
	s_nop 0
	s_nop 0
	s_nop 0
	s_nop 0
	s_nop 0
	s_nop 0
	s_nop 0
	s_nop 0
	s_nop 0
	s_nop 0
	s_nop 0
	s_nop 0
	s_nop 0
	s_nop 0
	s_nop 0
	s_nop 0
	s_nop 0
	s_nop 0
	s_nop 0
	s_nop 0
	s_nop 0
	s_nop 0
	s_nop 0
	s_nop 0
	s_nop 0
	s_nop 0
	s_nop 0
	s_nop 0
	s_nop 0
	s_nop 0
	s_nop 0
	s_nop 0
	s_nop 0
	s_nop 0
	s_nop 0
	s_nop 0
	s_nop 0
	s_nop 0
	s_nop 0
	s_nop 0
	s_nop 0
	s_nop 0
	s_nop 0
	s_nop 0
	s_nop 0
	s_nop 0
	s_nop 0
	s_nop 0
	s_nop 0
	s_nop 0
	s_nop 0
	s_nop 0
	s_nop 0
	s_nop 0
	s_nop 0
	s_nop 0
	s_nop 0
	s_nop 0
	s_nop 0
	s_nop 0
	s_nop 0
	s_nop 0
	s_nop 0
	s_nop 0
	s_nop 0
	s_nop 0
	s_nop 0
	s_nop 0
	s_nop 0
	s_nop 0
	s_nop 0
	s_nop 0
	s_nop 0
	s_nop 0
	s_nop 0
	s_nop 0
	s_nop 0
	s_nop 0
	s_nop 0
	s_nop 0
	s_nop 0
	s_nop 0
	s_nop 0
	s_nop 0
	s_nop 0
	s_nop 0
	s_nop 0
	s_nop 0
	s_nop 0
	s_nop 0
	s_nop 0
	s_nop 0
	s_nop 0
	s_nop 0
	s_nop 0
	s_nop 0
	s_nop 0
	s_nop 0
	s_nop 0
	s_nop 0
	s_nop 0
	s_nop 0
	s_nop 0
	s_nop 0
	s_nop 0
	s_nop 0
	s_nop 0
	s_nop 0
	s_nop 0
	s_nop 0
	s_nop 0
	s_nop 0
	s_nop 0
	s_nop 0
	s_nop 0
	s_nop 0
	s_nop 0
	s_nop 0
	s_nop 0
	s_nop 0
	s_nop 0
	s_nop 0
	s_nop 0
	s_nop 0
	s_nop 0
	s_nop 0
	s_nop 0
	s_nop 0
	s_nop 0
	s_nop 0
	s_nop 0
	s_nop 0
	s_nop 0
	s_nop 0
	s_nop 0
	s_nop 0
	s_nop 0
	s_nop 0
	s_nop 0
	s_nop 0
	s_nop 0
	s_nop 0
	s_nop 0
	s_nop 0
	s_nop 0
	s_nop 0
	s_nop 0
	s_nop 0
	s_nop 0
	s_nop 0
	s_nop 0
	s_nop 0
	s_nop 0
	s_nop 0
	s_nop 0
	s_nop 0
	s_nop 0
	s_nop 0
	s_nop 0
	s_nop 0
	s_nop 0
	s_nop 0
	s_nop 0
	s_nop 0
	s_nop 0
	s_nop 0
	s_nop 0
	s_nop 0
	s_nop 0
	s_nop 0
	s_nop 0
	s_nop 0
	s_nop 0
	s_nop 0
	s_nop 0
	s_nop 0
	s_nop 0
	s_nop 0
	s_nop 0
	s_nop 0
	s_nop 0
	s_nop 0
	s_nop 0
	s_nop 0
	s_nop 0
	s_nop 0
	s_nop 0
	s_nop 0
	s_nop 0
	s_nop 0
	s_nop 0
	s_nop 0
	s_nop 0
	s_nop 0
	s_nop 0
	s_nop 0
	s_nop 0
	s_nop 0
	s_nop 0
	s_nop 0
	s_nop 0
	s_nop 0
	s_nop 0
	s_nop 0
	s_nop 0
	s_nop 0
	s_nop 0
	s_nop 0
	s_nop 0
	s_nop 0
	s_nop 0
	s_nop 0
	s_nop 0
	s_nop 0
	s_nop 0
	s_nop 0
	s_nop 0
	s_nop 0
	s_nop 0
	s_nop 0
	s_nop 0
	s_nop 0
	s_nop 0
	s_nop 0
	s_nop 0
	s_nop 0
	s_nop 0
	s_nop 0
	s_nop 0
	s_nop 0
	s_nop 0
	s_nop 0
	s_nop 0
	s_nop 0
	s_nop 0
	s_nop 0
	s_nop 0
	s_nop 0
	s_nop 0
	s_nop 0
	s_nop 0
	s_nop 0
	s_nop 0
	s_nop 0
	s_nop 0
	s_nop 0
	s_nop 0
	s_nop 0
	s_nop 0
	s_nop 0
	s_nop 0
	s_nop 0
	s_nop 0
	s_nop 0
	s_nop 0
	s_nop 0
	s_nop 0
	s_nop 0
	s_nop 0
	s_nop 0
	s_nop 0
	s_nop 0
	s_nop 0
	s_nop 0
	s_nop 0
	s_nop 0
	s_nop 0
	s_nop 0
	s_nop 0
	s_nop 0
	s_nop 0
	s_nop 0
	s_nop 0
	s_nop 0
	s_nop 0
	s_nop 0
	s_nop 0
	s_nop 0
	s_nop 0
	s_nop 0
	s_nop 0
	s_nop 0
	s_nop 0
	s_nop 0
	s_nop 0
	s_nop 0
	s_nop 0
	s_nop 0
	s_nop 0
	s_nop 0
	s_nop 0
	s_nop 0
	s_nop 0
	s_nop 0
	s_nop 0
	s_nop 0
	s_nop 0
	s_nop 0
	s_nop 0
	s_nop 0
	s_nop 0
	s_nop 0
	s_nop 0
	s_nop 0
	s_nop 0
	s_nop 0
	s_nop 0
	s_nop 0
	s_nop 0
	s_nop 0
	s_nop 0
	s_nop 0
	s_nop 0
	s_nop 0
	s_nop 0
	s_nop 0
	s_nop 0
	s_nop 0
	s_nop 0
	s_nop 0
	s_nop 0
	s_nop 0
	s_nop 0
	s_nop 0
	s_nop 0
	s_nop 0
	s_nop 0
	s_nop 0
	s_nop 0
	s_nop 0
	s_nop 0
	s_nop 0
	s_nop 0
	s_nop 0
	s_nop 0
	s_nop 0
	s_nop 0
	s_nop 0
	s_nop 0
	s_nop 0
	s_nop 0
	s_nop 0
	s_nop 0
	s_nop 0
	s_nop 0
	s_nop 0
	s_nop 0
	s_nop 0
	s_nop 0
	s_nop 0
	s_nop 0
	s_nop 0
	s_nop 0
	s_nop 0
	s_nop 0
	s_nop 0
	s_nop 0
	s_nop 0
	s_nop 0
	s_nop 0
	s_nop 0
	s_nop 0
	s_nop 0
	s_nop 0
	s_nop 0
	s_nop 0
	s_nop 0
	s_nop 0
	s_nop 0
	s_nop 0
	s_nop 0
	s_nop 0
	s_nop 0
	s_nop 0
	s_nop 0
	s_nop 0
	s_nop 0
	s_nop 0
	s_nop 0
	s_nop 0
	s_nop 0
	s_nop 0
	s_nop 0
	s_nop 0
	s_nop 0
	s_nop 0
	s_nop 0
	s_nop 0
	s_nop 0
	s_nop 0
	s_nop 0
	s_nop 0
	s_nop 0
	s_nop 0
	s_nop 0
	s_nop 0
	s_nop 0
	s_nop 0
	s_nop 0
	s_nop 0
	s_nop 0
	s_nop 0
	s_nop 0
	s_nop 0
	s_nop 0
	s_nop 0
	s_nop 0
	s_nop 0
	s_nop 0
	s_nop 0
	s_nop 0
	s_nop 0
	s_nop 0
	s_nop 0
	s_nop 0
	s_nop 0
	s_nop 0
	s_nop 0
	s_nop 0
	s_nop 0
	s_nop 0
	s_nop 0
	s_nop 0
	s_nop 0
	s_nop 0
	s_nop 0
	s_nop 0
	s_nop 0
	s_nop 0
